# drop phase 1 (adaLN finalize) + its grid barrier: finalize runs in phase 2, layer-0 norm sums the split-K partials itself via LDS exchange
# speedup vs baseline: 1.0342x; 1.0057x over previous
.LBB0_8:
	s_cmp_eq_u32 s14, 1
	s_cbranch_scc1 .Lam_island_683
	s_add_i32 s6, s14, -2
	s_cmp_gt_u32 s6, 19
	s_cselect_b64 s[0:1], -1, 0
	s_and_b64 vcc, exec, s[0:1]
	s_cbranch_vccnz .LBB0_10
	s_add_i32 s0, s14, -12
	s_cmp_lt_u32 s6, 10
	s_cselect_b32 s0, s6, s0
	s_cmp_lg_u32 s0, 7
	s_mov_b64 s[2:3], -1
	s_cselect_b64 s[0:1], -1, 0
	s_andn2_b64 vcc, exec, s[0:1]
	s_cbranch_vccz .LBB0_11
	s_getpc_b64 s[98:99]

.LBB0_11:
	s_mov_b32 s48, s93
	s_mov_b64 s[0:1], s[90:91]
	s_mov_b64 s[4:5], 0
	s_load_dwordx2 s[2:3], s[0:1], 0xb0
	s_load_dwordx16 s[52:67], s[0:1], 0x0
	s_mov_b64 s[40:41], -1
	s_mov_b64 s[10:11], 0
	s_waitcnt lgkmcnt(0)
	s_add_u32 s8, s2, s4
	v_writelane_b32 v253, s52, 63
	s_nop 1
	v_writelane_b32 v254, s53, 0
	v_writelane_b32 v254, s54, 1
	v_writelane_b32 v254, s55, 2
	v_writelane_b32 v254, s56, 3
	v_writelane_b32 v254, s57, 4
	v_writelane_b32 v254, s58, 5
	v_writelane_b32 v254, s59, 6
	v_writelane_b32 v254, s60, 7
	v_writelane_b32 v254, s61, 8
	v_writelane_b32 v254, s62, 9
	v_writelane_b32 v254, s63, 10
	v_writelane_b32 v254, s64, 11
	v_writelane_b32 v254, s65, 12
	v_writelane_b32 v254, s66, 13
	v_writelane_b32 v254, s67, 14
	s_load_dwordx16 s[52:67], s[0:1], 0x40
	s_waitcnt lgkmcnt(0)
	v_writelane_b32 v254, s52, 15
	s_nop 1
	v_writelane_b32 v254, s53, 16
	v_writelane_b32 v254, s54, 17
	v_writelane_b32 v254, s55, 18
	v_writelane_b32 v254, s56, 19
	v_writelane_b32 v254, s57, 20
	v_writelane_b32 v254, s58, 21
	v_writelane_b32 v254, s59, 22
	v_writelane_b32 v254, s60, 23
	v_writelane_b32 v254, s61, 24
	v_writelane_b32 v254, s62, 25
	v_writelane_b32 v254, s63, 26
	v_writelane_b32 v254, s64, 27
	v_writelane_b32 v254, s65, 28
	v_writelane_b32 v254, s66, 29
	v_writelane_b32 v254, s67, 30
	s_load_dwordx4 s[80:83], s[0:1], 0xa0
	s_load_dwordx8 s[52:59], s[0:1], 0x80
	s_mov_b64 s[0:1], 0
	s_waitcnt lgkmcnt(0)
	v_writelane_b32 v254, s52, 31
	s_nop 1
	v_writelane_b32 v254, s53, 32
	v_writelane_b32 v254, s54, 33
	v_writelane_b32 v254, s55, 34
	v_writelane_b32 v254, s56, 35
	v_writelane_b32 v254, s57, 36
	v_writelane_b32 v254, s58, 37
	v_writelane_b32 v254, s59, 38
	v_writelane_b32 v254, s2, 39
	s_addc_u32 s9, s3, s5
	s_nop 0
	v_writelane_b32 v254, s3, 40
	s_add_u32 s2, s8, 0x300000
	s_addc_u32 s3, s9, 0
	s_cmp_lt_i32 s14, 1
	s_cbranch_scc1 .LBB0_18
	s_cmp_eq_u32 s14, 2
	s_mov_b64 s[0:1], -1
	s_cbranch_scc0 .LBB0_17
	v_mov_b32_e32 v0, v203
	s_lshl_b32 s0, s48, 6
	v_readlane_b32 s1, v253, 0
	s_add_i32 s0, s0, s1
	v_add_u32_e32 v0, s0, v0
	v_cmp_gt_i32_e32 vcc, s78, v0
	s_and_saveexec_b64 s[0:1], vcc
	s_cbranch_execz .LBB0_16
	v_readlane_b32 s40, v253, 1
	v_readlane_b32 s41, v253, 2
	s_load_dword s7, s[40:41], 0x0
	s_add_u32 s40, s8, 0x100000
	v_readlane_b32 s52, v253, 63
	s_addc_u32 s41, s9, 0
	s_lshl_b64 s[42:43], s[4:5], 2
	s_waitcnt lgkmcnt(0)
	s_lshl_b32 s7, s7, 9
	v_readlane_b32 s64, v254, 11
	v_readlane_b32 s65, v254, 12
	s_add_u32 s42, s64, s42
	s_addc_u32 s43, s65, s43
	s_mov_b64 s[46:47], 0
	v_readlane_b32 s53, v254, 0
	v_readlane_b32 s54, v254, 1
	v_readlane_b32 s55, v254, 2
	v_readlane_b32 s56, v254, 3
	v_readlane_b32 s57, v254, 4
	v_readlane_b32 s58, v254, 5
	v_readlane_b32 s59, v254, 6
	v_readlane_b32 s60, v254, 7
	v_readlane_b32 s61, v254, 8
	v_readlane_b32 s62, v254, 9
	v_readlane_b32 s63, v254, 10
	v_readlane_b32 s66, v254, 13
	v_readlane_b32 s67, v254, 14

.LBB0_16:
	s_or_b64 exec, exec, s[0:1]
	s_mov_b64 s[0:1], -1

.LBB0_595:
	s_or_b64 exec, exec, s[40:41]
	s_add_i32 s2, s14, 7
	s_cmp_gt_u32 s2, 18
	s_cbranch_scc1 .LBB0_601
	v_readlane_b32 s2, v255, 63
	s_cmp_lg_u32 s2, 0
	s_cbranch_scc1 .LBB0_601
	s_lshl_b32 s2, s48, 3
	v_readlane_b32 s3, v253, 9
	s_add_i32 s2, s2, s3
	v_mov_b32_e32 v16, v203
	s_cmpk_gt_i32 s2, 0x3fff
	s_cbranch_scc1 .LBB0_601
	s_ashr_i32 s3, s2, 12
	s_mul_i32 s10, s3, 0x6000
	v_lshlrev_b32_e32 v100, 4, v203
	s_lshl_b32 s11, s48, 10
	v_add_u32_e32 v100, s11, v100
	v_readlane_b32 s98, v254, 11
	v_readlane_b32 s99, v254, 12
	s_nop 4
	global_load_dwordx4 v[104:107], v100, s[98:99]
	s_add_u32 s98, s8, s10
	s_addc_u32 s99, s9, 0
	s_add_u32 s98, s98, 0x100000
	s_addc_u32 s99, s99, 0
	global_load_dwordx4 v[108:111], v100, s[98:99]
	s_add_u32 s98, s98, 0x18000
	s_addc_u32 s99, s99, 0
	global_load_dwordx4 v[112:115], v100, s[98:99]
	s_add_u32 s98, s98, 0x18000
	s_addc_u32 s99, s99, 0
	global_load_dwordx4 v[116:119], v100, s[98:99]
	s_add_u32 s98, s98, 0x18000
	s_addc_u32 s99, s99, 0
	global_load_dwordx4 v[120:123], v100, s[98:99]
	s_add_u32 s98, s98, 0x18000
	s_addc_u32 s99, s99, 0
	global_load_dwordx4 v[124:127], v100, s[98:99]
	s_add_u32 s98, s98, 0x18000
	s_addc_u32 s99, s99, 0
	global_load_dwordx4 v[128:131], v100, s[98:99]
	s_add_u32 s98, s98, 0x18000
	s_addc_u32 s99, s99, 0
	global_load_dwordx4 v[132:135], v100, s[98:99]
	s_add_u32 s98, s98, 0x18000
	s_addc_u32 s99, s99, 0
	global_load_dwordx4 v[136:139], v100, s[98:99]
	s_add_u32 s98, s98, 0x18000
	s_addc_u32 s99, s99, 0
	s_waitcnt vmcnt(0)
	v_add_f32_e32 v104, v104, v108
	v_add_f32_e32 v105, v105, v109
	v_add_f32_e32 v106, v106, v110
	v_add_f32_e32 v107, v107, v111
	v_add_f32_e32 v104, v104, v112
	v_add_f32_e32 v105, v105, v113
	v_add_f32_e32 v106, v106, v114
	v_add_f32_e32 v107, v107, v115
	v_add_f32_e32 v104, v104, v116
	v_add_f32_e32 v105, v105, v117
	v_add_f32_e32 v106, v106, v118
	v_add_f32_e32 v107, v107, v119
	v_add_f32_e32 v104, v104, v120
	v_add_f32_e32 v105, v105, v121
	v_add_f32_e32 v106, v106, v122
	v_add_f32_e32 v107, v107, v123
	v_add_f32_e32 v104, v104, v124
	v_add_f32_e32 v105, v105, v125
	v_add_f32_e32 v106, v106, v126
	v_add_f32_e32 v107, v107, v127
	v_add_f32_e32 v104, v104, v128
	v_add_f32_e32 v105, v105, v129
	v_add_f32_e32 v106, v106, v130
	v_add_f32_e32 v107, v107, v131
	v_add_f32_e32 v104, v104, v132
	v_add_f32_e32 v105, v105, v133
	v_add_f32_e32 v106, v106, v134
	v_add_f32_e32 v107, v107, v135
	v_add_f32_e32 v104, v104, v136
	v_add_f32_e32 v105, v105, v137
	v_add_f32_e32 v106, v106, v138
	v_add_f32_e32 v107, v107, v139
	v_add_u32_e32 v101, 0x20000, v100
	ds_write_b128 v101, v[104:107]
	v_lshlrev_b32_e32 v102, 4, v203
	v_add_u32_e32 v102, 0x20000, v102
	s_waitcnt lgkmcnt(0)
	s_barrier
	v_lshlrev_b32_e32 v0, 4, v16
	v_readlane_b32 s10, v254, 45
	v_and_b32_e32 v64, 0x3f0, v0
	v_readlane_b32 s11, v254, 46
	s_nop 4
	global_load_dwordx4 v[0:3], v64, s[10:11]
	global_load_dwordx4 v[4:7], v64, s[10:11] offset:1024
	global_load_dwordx4 v[8:11], v64, s[10:11] offset:2048
	global_load_dwordx4 v[12:15], v64, s[10:11] offset:3072
	v_and_b32_e32 v17, 64, v203
	v_add_u32_e32 v17, 64, v17
	v_xor_b32_e32 v18, 1, v203
	v_cmp_lt_i32_e32 vcc, v18, v17
	s_lshl_b32 s40, s6, 6
	v_readlane_b32 s6, v254, 41
	v_cndmask_b32_e32 v18, v203, v18, vcc
	v_lshlrev_b32_e32 v58, 2, v18
	v_xor_b32_e32 v18, 2, v203
	v_cmp_lt_i32_e32 vcc, v18, v17
	v_readlane_b32 s7, v254, 42
	s_ashr_i32 s3, s2, 31
	v_cndmask_b32_e32 v18, v203, v18, vcc
	v_lshlrev_b32_e32 v59, 2, v18
	v_xor_b32_e32 v18, 4, v203
	v_cmp_lt_i32_e32 vcc, v18, v17
	v_lshl_add_u64 v[32:33], s[6:7], 0, v[64:65]
	s_lshl_b64 s[6:7], s[2:3], 12
	v_cndmask_b32_e32 v18, v203, v18, vcc
	v_lshlrev_b32_e32 v60, 2, v18
	v_xor_b32_e32 v18, 8, v203
	v_cmp_lt_i32_e32 vcc, v18, v17
	v_readlane_b32 s52, v253, 63
	v_readlane_b32 s10, v254, 43
	v_cndmask_b32_e32 v18, v203, v18, vcc
	v_lshlrev_b32_e32 v61, 2, v18
	v_xor_b32_e32 v18, 16, v203
	v_cmp_lt_i32_e32 vcc, v18, v17
	v_readlane_b32 s53, v254, 0
	v_readlane_b32 s11, v254, 44
	v_cndmask_b32_e32 v18, v203, v18, vcc
	v_lshlrev_b32_e32 v62, 2, v18
	v_xor_b32_e32 v18, 32, v203
	s_add_u32 s10, s52, s10
	v_cmp_lt_i32_e32 vcc, v18, v17
	s_addc_u32 s11, s53, s11
	s_add_u32 s6, s10, s6
	v_cndmask_b32_e32 v17, v203, v18, vcc
	v_and_b32_e32 v18, 63, v16
	v_lshlrev_b32_e32 v64, 4, v18
	s_addc_u32 s7, s11, s7
	v_lshlrev_b32_e32 v63, 2, v17
	v_lshl_add_u64 v[16:17], s[6:7], 0, v[64:65]
	s_mov_b64 s[6:7], 0x800
	s_ashr_i32 s41, s40, 31
	v_lshl_add_u64 v[36:37], v[16:17], 0, s[6:7]
	s_lshl_b64 s[10:11], s[40:41], 12
	s_lshl_b64 s[6:7], s[2:3], 11
	s_add_u32 s3, s4, s6
	s_addc_u32 s7, s5, s7
	v_readlane_b32 s42, v254, 39
	v_readlane_b32 s43, v254, 40
	s_add_u32 s6, s42, s3
	v_lshlrev_b32_e32 v64, 3, v18
	s_addc_u32 s7, s43, s7
	v_lshl_add_u64 v[16:17], s[6:7], 0, v[64:65]
	s_mov_b64 s[6:7], 0xba00400
	v_lshl_add_u64 v[34:35], v[32:33], 0, s[30:31]
	v_lshl_add_u64 v[38:39], v[16:17], 0, s[6:7]
	s_lshl_b64 s[42:43], s[40:41], 11
	v_readlane_b32 s54, v254, 1
	v_readlane_b32 s55, v254, 2
	v_readlane_b32 s56, v254, 3
	v_readlane_b32 s57, v254, 4
	v_readlane_b32 s58, v254, 5
	v_readlane_b32 s59, v254, 6
	v_readlane_b32 s60, v254, 7
	v_readlane_b32 s61, v254, 8
	v_readlane_b32 s62, v254, 9
	v_readlane_b32 s63, v254, 10
	v_readlane_b32 s64, v254, 11
	v_readlane_b32 s65, v254, 12
	v_readlane_b32 s66, v254, 13
	v_readlane_b32 s67, v254, 14
.LBB0_598:
	s_ashr_i32 s3, s2, 12
	v_mad_i64_i32 v[16:17], s[6:7], s3, v207, v[34:35]
	v_mad_i64_i32 v[28:29], s[6:7], s3, v207, v[32:33]
	ds_read_b128 v[40:43], v102 offset:4096
	ds_read_b128 v[44:47], v102 offset:5120
	ds_read_b128 v[48:51], v102 offset:6144
	ds_read_b128 v[52:55], v102 offset:7168
	ds_read_b128 v[16:19], v102
	ds_read_b128 v[20:23], v102 offset:1024
	ds_read_b128 v[24:27], v102 offset:2048
	ds_read_b128 v[28:31], v102 offset:3072
	s_mov_b64 s[46:47], 0
	s_waitcnt vmcnt(0) lgkmcnt(0)
	v_pk_add_f32 v[42:43], v[42:43], 1.0 op_sel_hi:[1,0]
	v_pk_add_f32 v[56:57], v[40:41], 1.0 op_sel_hi:[1,0]
	v_pk_add_f32 v[46:47], v[46:47], 1.0 op_sel_hi:[1,0]
	v_pk_add_f32 v[66:67], v[44:45], 1.0 op_sel_hi:[1,0]
	v_pk_add_f32 v[50:51], v[50:51], 1.0 op_sel_hi:[1,0]
	v_pk_add_f32 v[68:69], v[48:49], 1.0 op_sel_hi:[1,0]
	v_pk_add_f32 v[54:55], v[54:55], 1.0 op_sel_hi:[1,0]
	v_pk_add_f32 v[70:71], v[52:53], 1.0 op_sel_hi:[1,0]
	v_pk_mul_f32 v[40:41], v[2:3], v[42:43]
	v_pk_mul_f32 v[42:43], v[0:1], v[56:57]
	v_pk_mul_f32 v[44:45], v[6:7], v[46:47]
	v_pk_mul_f32 v[46:47], v[4:5], v[66:67]
	v_pk_mul_f32 v[48:49], v[10:11], v[50:51]
	v_pk_mul_f32 v[50:51], v[8:9], v[68:69]
	v_pk_mul_f32 v[52:53], v[14:15], v[54:55]
	v_pk_mul_f32 v[54:55], v[12:13], v[70:71]
	v_mov_b64_e32 v[56:57], v[36:37]
